# e27: HGRN output loop - LDS staging writes wait vmcnt(12) (set loaded 3 steps earlier) instead of draining vmcnt to 0..5 every step
# speedup vs baseline: 1.0067x; 1.0067x over previous
; __device__ __forceinline__ unsigned cvt_pk_bf16(float lo, float hi) { unsigned r; asm volatile("v_cvt_pk_bf16_f32 %0, %1, %2" : "=v"(r) : "v"(lo), "v"(hi)); return r; }
; __device__ __forceinline__ float bf2f(unsigned short b) { return __uint_as_float(((unsigned)b) << 16); }
; #define LDS_WAIT() asm volatile("s_waitcnt lgkmcnt(0)" ::: "memory")
; #define HG_LOAD(j, s_) do { rl[j] = *(const u32x2*)(plf + (size_t)(s_) * 16 * D); if (FULL || !lo4) rb0[j] = *(const bf16x8*)(pb0 + (size_t)(s_) * 16 * D); if (FULL && lo4) rb1[j] = *(const bf16x8*)(pb1 + (size_t)(s_) * 16 * D); } while (0)
; template <bool FULL>
; __device__ __forceinline__ void hgrn_prep(char* lds, int s, int w, int kc, int tq, int kpos, float& gsum, s16x4& vfrag, u32x2& gvp) {
;     ...
;     for (int j = 0; j < 4; ++j) { const float kk = 1.f - __builtin_amdgcn_exp2f(lf[j]);
;         kd[j] = kk * __builtin_amdgcn_exp2f(glast - G[j]);
;         if (FULL) { const float qg = bf2f(qv[j]) * __builtin_amdgcn_exp2f(G[j]), kg = kk * __builtin_amdgcn_exp2f(fminf(-G[j], 115.f));
;             const unsigned qk = cvt_pk_bf16(qg, kg);
;             *(bf16*)(QG + (4 * tq + j) * ROWB + kpos * 2) = (bf16)(qk & 0xffffu);
;             *(bf16*)(KG + (4 * tq + j) * ROWB + kpos * 2) = (bf16)(qk >> 16); }
;         vfrag[j] = (short)vv[j]; }
;     { u32x2 kw; kw.x = cvt_pk_bf16(kd[0], kd[1]); kw.y = cvt_pk_bf16(kd[2], kd[3]); *(u32x2*)(KDT + ((16 * w + kc) * 16 + 4 * tq) * 2) = kw; }
;     DL[16 * w + kc] = __builtin_amdgcn_exp2f(glast);
;     gsum += glast;
;     if (FULL) { gvp.x = (unsigned)gv[0] | ((unsigned)gv[1] << 16); gvp.y = (unsigned)gv[2] | ((unsigned)gv[3] << 16); }
; }
; template <bool FULL, bool SBF> ...
;     ...
;     const float gn = FULL ? gain[16 * w + kc] : 0.f;
;     s16x4 vf_cur, vf_nxt; u32x2 gv_cur = {0u, 0u}, gv_nxt = {0u, 0u}, gv_prev = {0u, 0u}; f32x4 o_prev = {0.f, 0.f, 0.f, 0.f};
;     HG_LOAD(0, 0); if (1 < nsteps) HG_LOAD(1, 1); if (2 < nsteps) HG_LOAD(2, 2);
;     HG_WRITE(0, 0); if (1 < nsteps) HG_WRITE(1, 1);
;     if (3 < nsteps) HG_LOAD(0, 3); if (4 < nsteps) HG_LOAD(1, 4);
;     LDS_WAIT(); __builtin_amdgcn_s_barrier(); asm volatile("" ::: "memory");
;     hgrn_prep<FULL>(lds, 0, w, kc, tq, kpos, gsum, vf_cur, gv_cur);
;     LDS_WAIT(); __builtin_amdgcn_s_barrier(); asm volatile("" ::: "memory");
.LBB0_2341:
	s_or_b64 exec, exec, s[36:37]
	s_and_b32 s3, s83, 15
	s_lshl_b32 s10, s3, 8
	s_lshl_b32 s36, s3, 7
	s_ashr_i32 s3, s5, 2
	v_lshlrev_b32_e32 v53, 16, v45
	v_lshlrev_b32_e32 v45, 16, v86
	v_exp_f32_e32 v86, v110
	s_and_b32 s3, s3, 0x7fffffe0
	v_and_b32_e32 v28, 24, v28
	v_and_b32_e32 v30, 3, v80
	s_lshl_b32 s4, s4, 2
	v_or3_b32 v121, v28, v30, s3
	v_lshlrev_b32_e32 v36, 16, v58
	v_lshlrev_b32_e32 v58, 16, v81
	v_lshlrev_b32_e32 v40, 16, v83
	v_and_or_b32 v81, s4, 4, v121
	v_add_f32_e32 v83, v73, v110
	v_pk_add_f32 v[70:71], v[70:71], v[72:73]
	v_lshlrev_b32_e32 v52, 16, v44
	v_lshlrev_b32_e32 v54, 16, v46
	v_lshlrev_b32_e32 v44, 16, v85
	v_lshlrev_b32_e32 v46, 16, v87
	v_add_f32_e32 v85, v116, v73
	v_add_f32_e32 v72, v115, v73
	v_lshlrev_b32_e32 v73, 1, v81
	v_sub_f32_e32 v81, 1.0, v86
	v_sub_f32_e32 v86, v70, v83
	v_exp_f32_e32 v87, v83
	v_min_f32_e64 v83, -v83, s74
	v_exp_f32_e32 v86, v86
	v_exp_f32_e32 v83, v83
	v_lshlrev_b32_e32 v55, 16, v47
	v_lshlrev_b32_e32 v47, 16, v88
	s_waitcnt lgkmcnt(10)
	v_lshlrev_b32_e32 v88, 16, v114
	v_mul_f32_e32 v86, v81, v86
	v_mul_f32_e32 v87, v87, v88
	v_mul_f32_e32 v81, v81, v83
	v_mul_u32_u24_e32 v83, 0x440, v99
	v_cvt_pk_bf16_f32 v81, v87, v81
	v_exp_f32_e32 v87, v105
	v_add3_u32 v105, 0, v73, v83
	ds_write_b16 v105, v81
	ds_write_b16_d16_hi v105, v81 offset:8704
	v_sub_f32_e32 v81, v70, v85
	v_exp_f32_e32 v83, v85
	v_min_f32_e64 v85, -v85, s74
	v_exp_f32_e32 v81, v81
	v_exp_f32_e32 v85, v85
	v_sub_f32_e32 v73, 1.0, v87
	s_waitcnt lgkmcnt(10)
	v_lshlrev_b32_e32 v87, 16, v109
	v_mul_f32_e32 v81, v73, v81
	v_mul_f32_e32 v73, v73, v85
	v_exp_f32_e32 v85, v107
	v_mul_f32_e32 v83, v83, v87
	v_cvt_pk_bf16_f32 v73, v83, v73
	ds_write_b16 v105, v73 offset:272
	ds_write_b16_d16_hi v105, v73 offset:8976
	v_sub_f32_e32 v73, 1.0, v85
	v_sub_f32_e32 v83, v70, v71
	v_exp_f32_e32 v85, v71
	v_min_f32_e64 v71, -v71, s74
	v_exp_f32_e32 v83, v83
	v_exp_f32_e32 v71, v71
	s_waitcnt lgkmcnt(10)
	v_lshlrev_b32_e32 v87, 16, v108
	v_mul_f32_e32 v85, v85, v87
	v_mul_f32_e32 v83, v73, v83
	v_mul_f32_e32 v71, v73, v71
	v_exp_f32_e32 v73, v103
	v_cvt_pk_bf16_f32 v71, v85, v71
	ds_write_b16 v105, v71 offset:544
	ds_write_b16_d16_hi v105, v71 offset:9248
	v_exp_f32_e32 v85, v72
	v_sub_f32_e32 v71, 1.0, v73
	v_sub_f32_e32 v73, v70, v72
	v_min_f32_e64 v72, -v72, s74
	v_exp_f32_e32 v73, v73
	v_exp_f32_e32 v72, v72
	s_waitcnt lgkmcnt(10)
	v_lshlrev_b32_e32 v87, 16, v106
	v_exp_f32_e32 v70, v70
	v_mul_f32_e32 v73, v71, v73
	v_mul_f32_e32 v71, v71, v72
	v_mul_f32_e32 v85, v85, v87
	v_cvt_pk_bf16_f32 v71, v85, v71
	ds_write_b16 v105, v71 offset:816
	ds_write_b16_d16_hi v105, v71 offset:9520
	v_cvt_pk_bf16_f32 v72, v86, v81
	v_lshlrev_b32_e32 v71, 5, v68
	v_lshlrev_b32_e32 v81, 3, v99
	v_lshlrev_b32_e32 v104, 2, v99
	v_add3_u32 v106, 0, v71, v81
	v_lshl_add_u32 v107, v68, 2, 0
	v_lshl_add_u32 v108, v99, 4, 0
	v_cvt_pk_bf16_f32 v73, v83, v73
	ds_write_b64 v106, v[72:73] offset:17408
	ds_write_b32 v107, v70 offset:25600
	v_sub_u32_e32 v68, v108, v81
	v_or_b32_e32 v70, 2, v104
	v_mul_u32_u24_e32 v71, 0x78, v99
	v_cmp_gt_u32_e64 s[46:47], v70, v84
	v_or_b32_e32 v70, 3, v104
	v_lshl_add_u32 v109, v84, 5, v68
	v_add3_u32 v110, v68, v71, s4
	v_and_b32_e32 v68, 7, v80
	v_cmp_gt_u32_e64 s[48:49], v70, v84
	v_lshlrev_b32_e32 v70, 7, v99
	v_lshlrev_b32_e32 v68, 2, v68
	v_add3_u32 v103, 0, v68, v70
	v_and_b32_e32 v68, 31, v80
	v_perm_b32 v88, v111, v69, s35
	v_lshl_add_u64 v[60:61], v[60:61], 0, s[10:11]
	v_lshlrev_b32_e32 v68, 3, v68
	v_mov_b32_e32 v69, v3
	s_mov_b32 s37, s11
	v_lshl_add_u64 v[60:61], v[60:61], 0, v[68:69]
	s_add_i32 s2, s2, s6
	v_lshl_add_u64 v[80:81], s[58:59], 0, v[60:61]
	v_lshl_add_u64 v[60:61], v[64:65], 0, s[36:37]
	v_lshlrev_b32_e32 v28, 16, v59
	v_lshlrev_b32_e32 v59, 16, v82
	v_or_b32_e32 v82, s2, v84
	s_waitcnt lgkmcnt(0)
	s_barrier
	v_lshl_add_u64 v[60:61], v[60:61], 0, v[2:3]
	v_lshlrev_b64 v[62:63], 12, v[62:63]
	v_lshlrev_b32_e32 v2, 4, v84
	v_ashrrev_i32_e32 v83, 31, v82
	s_movk_i32 s2, 0x110
	v_lshlrev_b64 v[60:61], 1, v[60:61]
	v_or3_b32 v62, v62, s10, v2
	v_mov_b32_e32 v2, v3
	v_lshlrev_b32_e32 v29, 16, v29
	v_lshlrev_b32_e32 v30, 16, v31
	v_lshlrev_b32_e32 v31, 16, v43
	v_lshlrev_b32_e32 v32, 16, v50
	v_lshlrev_b32_e32 v33, 16, v51
	v_lshlrev_b32_e32 v34, 16, v56
	v_lshlrev_b32_e32 v35, 16, v57
	v_lshlrev_b32_e32 v37, 16, v42
	v_lshlrev_b32_e32 v38, 16, v96
	v_lshlrev_b32_e32 v39, 16, v97
	v_lshlrev_b32_e32 v56, 16, v48
	v_lshlrev_b32_e32 v57, 16, v49
	v_lshlrev_b32_e32 v41, 16, v93
	v_lshlrev_b32_e32 v42, 16, v94
	v_lshlrev_b32_e32 v43, 16, v95
	v_lshlrev_b32_e32 v48, 16, v89
	v_lshlrev_b32_e32 v49, 16, v90
	v_lshlrev_b32_e32 v50, 16, v91
	v_lshlrev_b32_e32 v51, 16, v92
	s_waitcnt lgkmcnt(10)
	v_perm_b32 v91, v120, v119, s35
	v_perm_b32 v90, v118, v117, s35
	v_cmp_gt_u32_e64 s[42:43], v104, v84
	v_cmp_lt_u32_e64 s[44:45], v104, v84
	v_cmp_eq_u32_e64 s[50:51], 2, v99
	v_cmp_gt_u32_e64 s[40:41], 8, v84
	v_lshl_add_u64 v[72:73], v[82:83], 1, s[12:13]
	v_perm_b32 v89, v113, v112, s35
	v_mad_u32_u24 v111, v84, s2, v108
	v_lshl_add_u64 v[82:83], v[66:67], 0, v[60:61]
	v_lshl_add_u64 v[84:85], s[58:59], 0, v[62:63]
	v_lshl_add_u64 v[86:87], s[58:59], 0, v[60:61]
	v_add_u32_e32 v112, s85, v104
	s_mov_b32 s10, 0
	v_mov_b32_e32 v60, v3
	v_mov_b32_e32 v61, v3
	v_mov_b32_e32 v62, v3
	v_mov_b32_e32 v63, v3
	s_mov_b64 s[2:3], 0
	s_mov_b32 s86, 0
	s_mov_b32 s87, 0
	v_mov_b64_e32 v[64:65], v[2:3]
	v_mov_b64_e32 v[92:93], v[2:3]
	s_waitcnt vmcnt(0)

.LBB0_2351:
	s_bitcmp1_b32 s87, 0
	s_cselect_b32 s4, 0x5000, 0
	s_add_i32 s4, s4, 0
	v_add_u32_e32 v60, s4, v100
	s_waitcnt vmcnt(12)
	ds_write_b64 v60, v[74:75] offset:28672
	s_waitcnt vmcnt(12)
	v_mov_b64_e32 v[62:63], v[14:15]
	v_mov_b32_e32 v64, 0x3000
	v_mov_b64_e32 v[60:61], v[12:13]
	s_and_saveexec_b64 s[62:63], s[38:39]
	v_add_u32_e32 v60, s4, v101
	ds_write_b128 v60, v[12:15] offset:36864
	v_mov_b64_e32 v[62:63], v[18:19]
	v_mov_b32_e32 v64, 0x4000
	v_mov_b64_e32 v[60:61], v[16:17]
	s_or_b64 exec, exec, s[62:63]
	v_add3_u32 v64, s4, v64, v101
	ds_write_b128 v64, v[60:63] offset:28672
	s_cmp_gt_u32 s87, 58
	s_cbranch_scc1 .LBB0_2360
	s_branch .LBB0_2357

.LBB0_2357:
	s_waitcnt vmcnt(12)
	v_lshl_add_u64 v[12:13], v[80:81], 0, s[2:3]
	v_add_co_u32_e32 v12, vcc, 0x28550000, v12
	s_nop 1
	v_addc_co_u32_e32 v13, vcc, 0, v13, vcc
	global_load_dwordx2 v[74:75], v[12:13], off
	v_lshl_add_u64 v[12:13], v[82:83], 0, s[2:3]
	v_add_co_u32_e32 v12, vcc, 0x50000, v12
	s_nop 1
	v_addc_co_u32_e32 v13, vcc, 0, v13, vcc
	global_load_dwordx4 v[12:15], v[12:13], off
	s_and_saveexec_b64 s[62:63], s[38:39]
	s_cbranch_execz .LBB0_2359
	v_lshl_add_u64 v[16:17], v[86:87], 0, s[2:3]
	v_add_co_u32_e32 v16, vcc, 0x34850000, v16
	s_nop 1
	v_addc_co_u32_e32 v17, vcc, 0, v17, vcc
	global_load_dwordx4 v[16:19], v[16:17], off

; __device__ __forceinline__ unsigned cvt_pk_bf16(float lo, float hi) { unsigned r; asm volatile("v_cvt_pk_bf16_f32 %0, %1, %2" : "=v"(r) : "v"(lo), "v"(hi)); return r; }
; __device__ __forceinline__ void hgrn_fin(char* lds, int s, int w, int kc, int tq, int ch, int row0, float gn, const f32x4 o, const u32x2 gvp, bf16* __restrict__ O) {
;     const float* SSQP = (const float*)(lds + SSQP_OFF + (s & 1) * 512);
; #pragma unroll
;     for (int i = 0; i < 4; ++i) { const float part = SSQP[(4 * tq + i) * 8 + (kc & 7)];
;         const float tot = row16_sum(kc < 8 ? part : 0.f);
;         const float rs = __builtin_amdgcn_rsqf(tot * (1.f / 128.f) + EPS);
;         const unsigned gw_ = i < 2 ? gvp.x : gvp.y; const float gate = __uint_as_float((i & 1) ? (gw_ & 0xffff0000u) : (gw_ << 16));
;         const float ov = o[i] * rs * gn * gate;
;         O[(size_t)(row0 + 16 * s + 4 * tq + i) * D + ch] = (bf16)(cvt_pk_bf16(ov, 0.f) & 0xffffu); }
; }
.LBB0_2369:
	s_and_b32 s5, s10, 0x200
	v_add_u32_e32 v62, s5, v103
	ds_read_b32 v60, v62 offset:26624
	v_lshlrev_b32_e32 v61, 16, v90
	v_ashrrev_i32_e32 v95, 31, v94
	s_cmp_gt_u32 s87, 60
	s_waitcnt lgkmcnt(0)
	v_cndmask_b32_e64 v60, 0, v60, s[40:41]
	s_nop 1
	v_add_f32_dpp v60, v60, v60 row_ror:8 row_mask:0xf bank_mask:0xf bound_ctrl:1
	s_nop 1
	v_add_f32_dpp v60, v60, v60 row_ror:4 row_mask:0xf bank_mask:0xf bound_ctrl:1
	s_nop 1
	v_add_f32_dpp v60, v60, v60 row_ror:2 row_mask:0xf bank_mask:0xf bound_ctrl:1
	s_nop 1
	v_add_f32_dpp v60, v60, v60 row_ror:1 row_mask:0xf bank_mask:0xf bound_ctrl:1
	v_fmamk_f32 v60, v60, 0x3c000000, v198
	v_rsq_f32_e32 v60, v60
	s_nop 0
	v_mul_f32_e32 v60, v68, v60
	v_mul_f32_e32 v60, v98, v60
	v_mul_f32_e32 v60, v60, v61
	v_cvt_pk_bf16_f32 v63, v60, v3
	v_lshlrev_b64 v[60:61], 12, v[94:95]
	v_lshl_add_u64 v[60:61], v[72:73], 0, v[60:61]
	global_store_short v[60:61], v63, off
	ds_read_b32 v60, v62 offset:26656
	v_and_b32_e32 v61, 0xffff0000, v90
	s_waitcnt lgkmcnt(0)
	v_cndmask_b32_e64 v60, 0, v60, s[40:41]
	s_nop 1
	v_add_f32_dpp v60, v60, v60 row_ror:8 row_mask:0xf bank_mask:0xf bound_ctrl:1
	s_nop 1
	v_add_f32_dpp v60, v60, v60 row_ror:4 row_mask:0xf bank_mask:0xf bound_ctrl:1
	s_nop 1
	v_add_f32_dpp v60, v60, v60 row_ror:2 row_mask:0xf bank_mask:0xf bound_ctrl:1
	s_nop 1
	v_add_f32_dpp v60, v60, v60 row_ror:1 row_mask:0xf bank_mask:0xf bound_ctrl:1
	v_fmamk_f32 v60, v60, 0x3c000000, v198
	v_rsq_f32_e32 v60, v60
	s_nop 0
	v_mul_f32_e32 v60, v69, v60
	v_mul_f32_e32 v60, v98, v60
	v_mul_f32_e32 v60, v60, v61
	v_cvt_pk_bf16_f32 v63, v60, v3
	v_add_u32_e32 v60, 1, v94
	v_ashrrev_i32_e32 v61, 31, v60
	v_lshlrev_b64 v[60:61], 12, v[60:61]
	v_lshl_add_u64 v[60:61], v[72:73], 0, v[60:61]
	global_store_short v[60:61], v63, off
	ds_read_b32 v60, v62 offset:26688
	v_lshlrev_b32_e32 v61, 16, v91
	s_waitcnt lgkmcnt(0)
	v_cndmask_b32_e64 v60, 0, v60, s[40:41]
	s_nop 1
	v_add_f32_dpp v60, v60, v60 row_ror:8 row_mask:0xf bank_mask:0xf bound_ctrl:1
	s_nop 1
	v_add_f32_dpp v60, v60, v60 row_ror:4 row_mask:0xf bank_mask:0xf bound_ctrl:1
	s_nop 1
	v_add_f32_dpp v60, v60, v60 row_ror:2 row_mask:0xf bank_mask:0xf bound_ctrl:1
	s_nop 1
	v_add_f32_dpp v60, v60, v60 row_ror:1 row_mask:0xf bank_mask:0xf bound_ctrl:1
	v_fmamk_f32 v60, v60, 0x3c000000, v198
	v_rsq_f32_e32 v60, v60
	s_nop 0
	v_mul_f32_e32 v60, v70, v60
	v_mul_f32_e32 v60, v98, v60
	v_mul_f32_e32 v60, v60, v61
	v_cvt_pk_bf16_f32 v63, v60, v3
	v_add_u32_e32 v60, 2, v94
	v_ashrrev_i32_e32 v61, 31, v60
	v_lshlrev_b64 v[60:61], 12, v[60:61]
	v_lshl_add_u64 v[60:61], v[72:73], 0, v[60:61]
	global_store_short v[60:61], v63, off
	ds_read_b32 v60, v62 offset:26720
	v_and_b32_e32 v61, 0xffff0000, v91
	s_waitcnt lgkmcnt(0)
	v_cndmask_b32_e64 v60, 0, v60, s[40:41]
	s_nop 1
	v_add_f32_dpp v60, v60, v60 row_ror:8 row_mask:0xf bank_mask:0xf bound_ctrl:1
	s_nop 1
	v_add_f32_dpp v60, v60, v60 row_ror:4 row_mask:0xf bank_mask:0xf bound_ctrl:1
	s_nop 1
	v_add_f32_dpp v60, v60, v60 row_ror:2 row_mask:0xf bank_mask:0xf bound_ctrl:1
	s_nop 1
	v_add_f32_dpp v60, v60, v60 row_ror:1 row_mask:0xf bank_mask:0xf bound_ctrl:1
	v_fmamk_f32 v60, v60, 0x3c000000, v198
	v_rsq_f32_e32 v60, v60
	s_nop 0
	v_mul_f32_e32 v60, v71, v60
	v_mul_f32_e32 v60, v98, v60
	v_mul_f32_e32 v60, v60, v61
	v_cvt_pk_bf16_f32 v62, v60, v3
	v_add_u32_e32 v60, 3, v94
	v_ashrrev_i32_e32 v61, 31, v60
	v_lshlrev_b64 v[60:61], 12, v[60:61]
	v_lshl_add_u64 v[60:61], v[72:73], 0, v[60:61]
	global_store_short v[60:61], v62, off
	s_cbranch_scc1 .LBB0_2373
	s_bitcmp1_b32 s4, 0
	s_cselect_b32 s4, 0x5000, 0
	s_add_i32 s4, s4, 0
	v_add_u32_e32 v60, s4, v100
	s_waitcnt vmcnt(12)
	ds_write_b64 v60, v[76:77] offset:28672
	s_waitcnt vmcnt(12)
	v_mov_b64_e32 v[62:63], v[22:23]
	v_mov_b32_e32 v68, 0x3000
	v_mov_b64_e32 v[60:61], v[20:21]
	s_and_saveexec_b64 s[36:37], s[38:39]
	v_add_u32_e32 v60, s4, v101
	ds_write_b128 v60, v[20:23] offset:36864
	v_mov_b64_e32 v[62:63], v[6:7]
	v_mov_b32_e32 v68, 0x4000
	v_mov_b64_e32 v[60:61], v[4:5]
	s_or_b64 exec, exec, s[36:37]
	v_add3_u32 v68, s4, v68, v101
	ds_write_b128 v68, v[60:63] offset:28672
.LBB0_2373:
	s_cmp_gt_u32 s87, 57
	s_cbranch_scc1 .LBB0_2377
	s_waitcnt vmcnt(12)
	v_lshl_add_u64 v[20:21], v[80:81], 0, s[2:3]
	v_add_co_u32_e32 v20, vcc, 0x28560000, v20
	s_nop 1
	v_addc_co_u32_e32 v21, vcc, 0, v21, vcc
	global_load_dwordx2 v[76:77], v[20:21], off
	v_lshl_add_u64 v[20:21], v[82:83], 0, s[2:3]
	v_add_co_u32_e32 v20, vcc, 0x60000, v20
	s_nop 1
	v_addc_co_u32_e32 v21, vcc, 0, v21, vcc
	global_load_dwordx4 v[20:23], v[20:21], off
	s_and_saveexec_b64 s[36:37], s[38:39]
	s_cbranch_execz .LBB0_2376
	v_lshl_add_u64 v[4:5], v[86:87], 0, s[2:3]
	v_add_co_u32_e32 v4, vcc, 0x34860000, v4
	s_nop 1
	v_addc_co_u32_e32 v5, vcc, 0, v5, vcc
	global_load_dwordx4 v[4:7], v[4:5], off

; __device__ __forceinline__ unsigned cvt_pk_bf16(float lo, float hi) { unsigned r; asm volatile("v_cvt_pk_bf16_f32 %0, %1, %2" : "=v"(r) : "v"(lo), "v"(hi)); return r; }
; __device__ __forceinline__ void hgrn_fin(char* lds, int s, int w, int kc, int tq, int ch, int row0, float gn, const f32x4 o, const u32x2 gvp, bf16* __restrict__ O) {
;     const float* SSQP = (const float*)(lds + SSQP_OFF + (s & 1) * 512);
; #pragma unroll
;     for (int i = 0; i < 4; ++i) { const float part = SSQP[(4 * tq + i) * 8 + (kc & 7)];
;         const float tot = row16_sum(kc < 8 ? part : 0.f);
;         const float rs = __builtin_amdgcn_rsqf(tot * (1.f / 128.f) + EPS);
;         const unsigned gw_ = i < 2 ? gvp.x : gvp.y; const float gate = __uint_as_float((i & 1) ? (gw_ & 0xffff0000u) : (gw_ << 16));
;         const float ov = o[i] * rs * gn * gate;
;         O[(size_t)(row0 + 16 * s + 4 * tq + i) * D + ch] = (bf16)(cvt_pk_bf16(ov, 0.f) & 0xffffu); }
; }
.LBB0_2388:
	s_add_i32 s4, s10, 0x200
	s_and_b32 s4, s4, 0x200
	v_add_u32_e32 v2, s4, v103
	ds_read_b32 v69, v2 offset:26624
	v_add_u32_e32 v68, 16, v94
	v_lshlrev_b32_e32 v70, 16, v90
	s_cmp_gt_u32 s87, 59
	s_mov_b64 s[88:89], 0x800
	s_waitcnt lgkmcnt(0)
	v_cndmask_b32_e64 v69, 0, v69, s[40:41]
	s_nop 1
	v_add_f32_dpp v69, v69, v69 row_ror:8 row_mask:0xf bank_mask:0xf bound_ctrl:1
	s_nop 1
	v_add_f32_dpp v69, v69, v69 row_ror:4 row_mask:0xf bank_mask:0xf bound_ctrl:1
	s_nop 1
	v_add_f32_dpp v69, v69, v69 row_ror:2 row_mask:0xf bank_mask:0xf bound_ctrl:1
	s_nop 1
	v_add_f32_dpp v69, v69, v69 row_ror:1 row_mask:0xf bank_mask:0xf bound_ctrl:1
	v_fmamk_f32 v69, v69, 0x3c000000, v198
	v_rsq_f32_e32 v69, v69
	s_nop 0
	v_mul_f32_e32 v64, v64, v69
	v_mul_f32_e32 v64, v98, v64
	v_ashrrev_i32_e32 v69, 31, v68
	v_mul_f32_e32 v64, v64, v70
	v_lshlrev_b64 v[68:69], 12, v[68:69]
	v_cvt_pk_bf16_f32 v64, v64, v3
	v_lshl_add_u64 v[68:69], v[72:73], 0, v[68:69]
	global_store_short v[68:69], v64, off
	ds_read_b32 v64, v2 offset:26656
	v_and_b32_e32 v68, 0xffff0000, v90
	s_waitcnt lgkmcnt(0)
	v_cndmask_b32_e64 v64, 0, v64, s[40:41]
	s_nop 1
	v_add_f32_dpp v64, v64, v64 row_ror:8 row_mask:0xf bank_mask:0xf bound_ctrl:1
	s_nop 1
	v_add_f32_dpp v64, v64, v64 row_ror:4 row_mask:0xf bank_mask:0xf bound_ctrl:1
	s_nop 1
	v_add_f32_dpp v64, v64, v64 row_ror:2 row_mask:0xf bank_mask:0xf bound_ctrl:1
	s_nop 1
	v_add_f32_dpp v64, v64, v64 row_ror:1 row_mask:0xf bank_mask:0xf bound_ctrl:1
	v_fmamk_f32 v64, v64, 0x3c000000, v198
	v_rsq_f32_e32 v64, v64
	s_nop 0
	v_mul_f32_e32 v64, v65, v64
	v_mul_f32_e32 v64, v98, v64
	v_mul_f32_e32 v64, v64, v68
	v_cvt_pk_bf16_f32 v68, v64, v3
	v_add_u32_e32 v64, 17, v94
	v_ashrrev_i32_e32 v65, 31, v64
	v_lshlrev_b64 v[64:65], 12, v[64:65]
	v_lshl_add_u64 v[64:65], v[72:73], 0, v[64:65]
	global_store_short v[64:65], v68, off
	ds_read_b32 v64, v2 offset:26688
	v_lshlrev_b32_e32 v65, 16, v91
	s_waitcnt lgkmcnt(0)
	v_cndmask_b32_e64 v64, 0, v64, s[40:41]
	s_nop 1
	v_add_f32_dpp v64, v64, v64 row_ror:8 row_mask:0xf bank_mask:0xf bound_ctrl:1
	s_nop 1
	v_add_f32_dpp v64, v64, v64 row_ror:4 row_mask:0xf bank_mask:0xf bound_ctrl:1
	s_nop 1
	v_add_f32_dpp v64, v64, v64 row_ror:2 row_mask:0xf bank_mask:0xf bound_ctrl:1
	s_nop 1
	v_add_f32_dpp v64, v64, v64 row_ror:1 row_mask:0xf bank_mask:0xf bound_ctrl:1
	v_fmamk_f32 v64, v64, 0x3c000000, v198
	v_rsq_f32_e32 v64, v64
	s_nop 0
	v_mul_f32_e32 v64, v66, v64
	v_mul_f32_e32 v64, v98, v64
	v_mul_f32_e32 v64, v64, v65
	v_cvt_pk_bf16_f32 v66, v64, v3
	ds_read_b32 v2, v2 offset:26720
	v_add_u32_e32 v64, 18, v94
	v_ashrrev_i32_e32 v65, 31, v64
	v_lshlrev_b64 v[64:65], 12, v[64:65]
	v_lshl_add_u64 v[64:65], v[72:73], 0, v[64:65]
	s_waitcnt lgkmcnt(0)
	v_cndmask_b32_e64 v2, 0, v2, s[40:41]
	global_store_short v[64:65], v66, off
	v_and_b32_e32 v64, 0xffff0000, v91
	v_add_f32_dpp v2, v2, v2 row_ror:8 row_mask:0xf bank_mask:0xf bound_ctrl:1
	s_nop 1
	v_add_f32_dpp v2, v2, v2 row_ror:4 row_mask:0xf bank_mask:0xf bound_ctrl:1
	s_nop 1
	v_add_f32_dpp v2, v2, v2 row_ror:2 row_mask:0xf bank_mask:0xf bound_ctrl:1
	s_nop 1
	v_add_f32_dpp v2, v2, v2 row_ror:1 row_mask:0xf bank_mask:0xf bound_ctrl:1
	v_fmamk_f32 v2, v2, 0x3c000000, v198
	v_rsq_f32_e32 v2, v2
	s_nop 0
	v_mul_f32_e32 v2, v67, v2
	v_mul_f32_e32 v2, v98, v2
	v_mul_f32_e32 v2, v2, v64
	v_add_u32_e32 v64, 19, v94
	v_ashrrev_i32_e32 v65, 31, v64
	v_lshlrev_b64 v[64:65], 12, v[64:65]
	v_lshl_add_u64 v[64:65], v[72:73], 0, v[64:65]
	v_cvt_pk_bf16_f32 v2, v2, v3
	global_store_short v[64:65], v2, off
	s_cbranch_scc1 .LBB0_2392
	s_bitcmp1_b32 s87, 0
	s_cselect_b32 s4, 0x5000, 0
	s_add_i32 s4, s4, 0
	v_add_u32_e32 v2, s4, v100
	s_waitcnt vmcnt(12)
	v_mov_b64_e32 v[66:67], v[26:27]
	ds_write_b64 v2, v[78:79] offset:28672
	v_mov_b32_e32 v2, 0x3000
	v_mov_b64_e32 v[64:65], v[24:25]
	s_and_saveexec_b64 s[36:37], s[38:39]
	v_add_u32_e32 v2, s4, v101
	v_mov_b64_e32 v[66:67], v[10:11]
	ds_write_b128 v2, v[24:27] offset:36864
	v_mov_b32_e32 v2, 0x4000
	v_mov_b64_e32 v[64:65], v[8:9]
	s_or_b64 exec, exec, s[36:37]
	v_add3_u32 v2, s4, v2, v101
	ds_write_b128 v2, v[64:67] offset:28672
.LBB0_2392:
	s_cmp_gt_u32 s87, 56
	s_cbranch_scc1 .LBB0_2396
	s_waitcnt vmcnt(12)
	v_lshl_add_u64 v[24:25], v[80:81], 0, s[2:3]
	v_add_co_u32_e32 v24, vcc, 0x28570000, v24
	s_nop 1
	v_addc_co_u32_e32 v25, vcc, 0, v25, vcc
	global_load_dwordx2 v[78:79], v[24:25], off
	v_lshl_add_u64 v[24:25], v[82:83], 0, s[2:3]
	v_add_co_u32_e32 v24, vcc, 0x70000, v24
	s_nop 1
	v_addc_co_u32_e32 v25, vcc, 0, v25, vcc
	global_load_dwordx4 v[24:27], v[24:25], off
	s_and_saveexec_b64 s[36:37], s[38:39]
	s_cbranch_execz .LBB0_2395
	v_lshl_add_u64 v[8:9], v[84:85], 0, s[2:3]
	v_add_co_u32_e32 v8, vcc, 0x34870000, v8
	s_nop 1
	v_addc_co_u32_e32 v9, vcc, 0, v9, vcc
	global_load_dwordx4 v[8:11], v[8:9], off
